# nt hint on P0/P3 streams plus the w_o epilogue's once-read x (f32 residual) loads
# speedup vs baseline: 1.0159x; 1.0049x over previous
.LBB0_1137:
	v_sub_u32_e32 v140, v162, v1
	s_mov_b32 s99, s50
	v_readfirstlane_b32 s98, v140
	s_lshr_b32 s98, s98, 8
	v_lshlrev_b32_e32 v134, 2, v1
	v_lshlrev_b32_e32 v135, 14, v1
	v_lshlrev_b32_e32 v136, 13, v1
	v_lshlrev_b32_e32 v137, 12, v1
	v_lshl_add_u32 v135, v180, 2, v135
	v_lshl_add_u32 v136, v180, 1, v136
	v_add_u32_e32 v137, v137, v180
	v_xor_b32_e32 v138, 16, v184
	v_xor_b32_e32 v139, 32, v184
	v_lshlrev_b32_e32 v138, 2, v138
	v_lshlrev_b32_e32 v139, 2, v139
	s_lshl_b32 s12, s98, 10
	s_add_u32 s14, s36, s12
	s_addc_u32 s15, s37, 0
	s_add_u32 s16, s30, s12
	s_addc_u32 s17, s31, 0
	s_lshl_b32 s12, s98, 22
	s_lshl_b32 s13, s99, 10
	s_add_u32 s12, s12, s13
	s_add_u32 s84, s22, s12
	s_addc_u32 s85, s23, 0
	s_lshr_b32 s13, s12, 1
	s_add_u32 s86, s26, s13
	s_addc_u32 s87, s27, 0
	s_lshr_b32 s13, s12, 2
	s_add_u32 s88, s34, s13
	s_addc_u32 s89, s35, 0
	global_load_dword v162, v134, s[14:15]
	global_load_dwordx4 v[186:189], v135, s[84:85]
	global_load_dwordx4 v[190:193], v135, s[84:85] offset:16
	global_load_dwordx4 v[194:197], v135, s[84:85] offset:512
	global_load_dwordx4 v[198:201], v135, s[84:85] offset:528
	s_add_u32 s84, s84, 0x40000
	s_addc_u32 s85, s85, 0
	global_load_dword v163, v134, s[14:15] offset:64
	global_load_dwordx4 v[202:205], v135, s[84:85]
	global_load_dwordx4 v[206:209], v135, s[84:85] offset:16
	global_load_dwordx4 v[210:213], v135, s[84:85] offset:512
	global_load_dwordx4 v[214:217], v135, s[84:85] offset:528
	s_add_u32 s84, s84, 0x40000
	s_addc_u32 s85, s85, 0
	s_waitcnt vmcnt(5)
	v_mul_f32_e32 v228, 0x41e1c71c, v162
	v_pk_add_f32 v[130:131], v[130:131], v[186:187]
	v_pk_add_f32 v[132:133], v[132:133], v[188:189]
	v_cvt_pk_bf16_f32 v218, v130, v131
	v_cvt_pk_bf16_f32 v219, v132, v133
	v_mul_f32_e32 v164, v228, v130
	v_mul_f32_e32 v165, v228, v131
	v_mul_f32_e32 v166, v228, v132
	v_mul_f32_e32 v167, v228, v133
	v_rndne_f32_e32 v164, v164
	v_rndne_f32_e32 v165, v165
	v_rndne_f32_e32 v166, v166
	v_rndne_f32_e32 v167, v167
	v_med3_f32 v164, v164, s71, v183
	v_med3_f32 v165, v165, s71, v183
	v_med3_f32 v166, v166, s71, v183
	v_med3_f32 v167, v167, s71, v183
	v_cvt_i32_f32_e32 v164, v164
	v_cvt_i32_f32_e32 v165, v165
	v_cvt_i32_f32_e32 v166, v166
	v_cvt_i32_f32_e32 v167, v167
	v_and_b32_e32 v164, 0xff, v164
	v_and_b32_e32 v165, 0xff, v165
	v_and_b32_e32 v166, 0xff, v166
	v_lshl_or_b32 v164, v165, 8, v164
	v_lshl_or_b32 v164, v166, 16, v164
	v_lshl_or_b32 v222, v167, 24, v164
	v_pk_mul_f32 v[224:225], v[130:131], v[130:131]
	v_pk_mul_f32 v[226:227], v[132:133], v[132:133]
	v_pk_add_f32 v[126:127], v[126:127], v[190:191]
	v_pk_add_f32 v[128:129], v[128:129], v[192:193]
	v_cvt_pk_bf16_f32 v220, v126, v127
	v_cvt_pk_bf16_f32 v221, v128, v129
	v_mul_f32_e32 v164, v228, v126
	v_mul_f32_e32 v165, v228, v127
	v_mul_f32_e32 v166, v228, v128
	v_mul_f32_e32 v167, v228, v129
	v_rndne_f32_e32 v164, v164
	v_rndne_f32_e32 v165, v165
	v_rndne_f32_e32 v166, v166
	v_rndne_f32_e32 v167, v167
	v_med3_f32 v164, v164, s71, v183
	v_med3_f32 v165, v165, s71, v183
	v_med3_f32 v166, v166, s71, v183
	v_med3_f32 v167, v167, s71, v183
	v_cvt_i32_f32_e32 v164, v164
	v_cvt_i32_f32_e32 v165, v165
	v_cvt_i32_f32_e32 v166, v166
	v_cvt_i32_f32_e32 v167, v167
	v_and_b32_e32 v164, 0xff, v164
	v_and_b32_e32 v165, 0xff, v165
	v_and_b32_e32 v166, 0xff, v166
	v_lshl_or_b32 v164, v165, 8, v164
	v_lshl_or_b32 v164, v166, 16, v164
	v_lshl_or_b32 v223, v167, 24, v164
	v_pk_fma_f32 v[224:225], v[126:127], v[126:127], v[224:225]
	v_pk_fma_f32 v[226:227], v[128:129], v[128:129], v[226:227]
	global_store_dwordx4 v136, v[218:221], s[86:87]
	global_store_dwordx2 v137, v[222:223], s[88:89]
	s_nop 0
	v_pk_add_f32 v[122:123], v[122:123], v[194:195]
	v_pk_add_f32 v[124:125], v[124:125], v[196:197]
	v_cvt_pk_bf16_f32 v218, v122, v123
	v_cvt_pk_bf16_f32 v219, v124, v125
	v_mul_f32_e32 v164, v228, v122
	v_mul_f32_e32 v165, v228, v123
	v_mul_f32_e32 v166, v228, v124
	v_mul_f32_e32 v167, v228, v125
	v_rndne_f32_e32 v164, v164
	v_rndne_f32_e32 v165, v165
	v_rndne_f32_e32 v166, v166
	v_rndne_f32_e32 v167, v167
	v_med3_f32 v164, v164, s71, v183
	v_med3_f32 v165, v165, s71, v183
	v_med3_f32 v166, v166, s71, v183
	v_med3_f32 v167, v167, s71, v183
	v_cvt_i32_f32_e32 v164, v164
	v_cvt_i32_f32_e32 v165, v165
	v_cvt_i32_f32_e32 v166, v166
	v_cvt_i32_f32_e32 v167, v167
	v_and_b32_e32 v164, 0xff, v164
	v_and_b32_e32 v165, 0xff, v165
	v_and_b32_e32 v166, 0xff, v166
	v_lshl_or_b32 v164, v165, 8, v164
	v_lshl_or_b32 v164, v166, 16, v164
	v_lshl_or_b32 v222, v167, 24, v164
	v_pk_fma_f32 v[224:225], v[122:123], v[122:123], v[224:225]
	v_pk_fma_f32 v[226:227], v[124:125], v[124:125], v[226:227]
	v_pk_add_f32 v[118:119], v[118:119], v[198:199]
	v_pk_add_f32 v[120:121], v[120:121], v[200:201]
	v_cvt_pk_bf16_f32 v220, v118, v119
	v_cvt_pk_bf16_f32 v221, v120, v121
	v_mul_f32_e32 v164, v228, v118
	v_mul_f32_e32 v165, v228, v119
	v_mul_f32_e32 v166, v228, v120
	v_mul_f32_e32 v167, v228, v121
	v_rndne_f32_e32 v164, v164
	v_rndne_f32_e32 v165, v165
	v_rndne_f32_e32 v166, v166
	v_rndne_f32_e32 v167, v167
	v_med3_f32 v164, v164, s71, v183
	v_med3_f32 v165, v165, s71, v183
	v_med3_f32 v166, v166, s71, v183
	v_med3_f32 v167, v167, s71, v183
	v_cvt_i32_f32_e32 v164, v164
	v_cvt_i32_f32_e32 v165, v165
	v_cvt_i32_f32_e32 v166, v166
	v_cvt_i32_f32_e32 v167, v167
	v_and_b32_e32 v164, 0xff, v164
	v_and_b32_e32 v165, 0xff, v165
	v_and_b32_e32 v166, 0xff, v166
	v_lshl_or_b32 v164, v165, 8, v164
	v_lshl_or_b32 v164, v166, 16, v164
	v_lshl_or_b32 v223, v167, 24, v164
	v_pk_fma_f32 v[224:225], v[118:119], v[118:119], v[224:225]
	v_pk_fma_f32 v[226:227], v[120:121], v[120:121], v[226:227]
	global_store_dwordx4 v136, v[218:221], s[86:87] offset:256
	global_store_dwordx2 v137, v[222:223], s[88:89] offset:128
	s_nop 0
	v_add_f32_e32 v224, v224, v225
	v_add_f32_e32 v226, v226, v227
	v_add_f32_e32 v224, v224, v226
	ds_bpermute_b32 v225, v138, v224
	s_waitcnt lgkmcnt(0)
	v_add_f32_e32 v224, v224, v225
	ds_bpermute_b32 v225, v139, v224
	s_waitcnt lgkmcnt(0)
	v_add_f32_e32 v224, v224, v225
	s_and_saveexec_b64 s[32:33], s[6:7]
	global_atomic_add_f32 v134, v224, s[16:17]
	s_or_b64 exec, exec, s[32:33]
	s_add_u32 s86, s86, 0x20000
	s_addc_u32 s87, s87, 0
	s_add_u32 s88, s88, 0x10000
	s_addc_u32 s89, s89, 0
	global_load_dword v162, v134, s[14:15] offset:128
	global_load_dwordx4 v[186:189], v135, s[84:85] nt
	global_load_dwordx4 v[190:193], v135, s[84:85] offset:16 nt
	global_load_dwordx4 v[194:197], v135, s[84:85] offset:512 nt
	global_load_dwordx4 v[198:201], v135, s[84:85] offset:528 nt
	s_add_u32 s84, s84, 0x40000
	s_addc_u32 s85, s85, 0
	s_waitcnt vmcnt(10)
	v_mul_f32_e32 v228, 0x41e1c71c, v163
	v_pk_add_f32 v[114:115], v[114:115], v[202:203]
	v_pk_add_f32 v[116:117], v[116:117], v[204:205]
	v_cvt_pk_bf16_f32 v218, v114, v115
	v_cvt_pk_bf16_f32 v219, v116, v117
	v_mul_f32_e32 v164, v228, v114
	v_mul_f32_e32 v165, v228, v115
	v_mul_f32_e32 v166, v228, v116
	v_mul_f32_e32 v167, v228, v117
	v_rndne_f32_e32 v164, v164
	v_rndne_f32_e32 v165, v165
	v_rndne_f32_e32 v166, v166
	v_rndne_f32_e32 v167, v167
	v_med3_f32 v164, v164, s71, v183
	v_med3_f32 v165, v165, s71, v183
	v_med3_f32 v166, v166, s71, v183
	v_med3_f32 v167, v167, s71, v183
	v_cvt_i32_f32_e32 v164, v164
	v_cvt_i32_f32_e32 v165, v165
	v_cvt_i32_f32_e32 v166, v166
	v_cvt_i32_f32_e32 v167, v167
	v_and_b32_e32 v164, 0xff, v164
	v_and_b32_e32 v165, 0xff, v165
	v_and_b32_e32 v166, 0xff, v166
	v_lshl_or_b32 v164, v165, 8, v164
	v_lshl_or_b32 v164, v166, 16, v164
	v_lshl_or_b32 v222, v167, 24, v164
	v_pk_mul_f32 v[224:225], v[114:115], v[114:115]
	v_pk_mul_f32 v[226:227], v[116:117], v[116:117]
	v_pk_add_f32 v[110:111], v[110:111], v[206:207]
	v_pk_add_f32 v[112:113], v[112:113], v[208:209]
	v_cvt_pk_bf16_f32 v220, v110, v111
	v_cvt_pk_bf16_f32 v221, v112, v113
	v_mul_f32_e32 v164, v228, v110
	v_mul_f32_e32 v165, v228, v111
	v_mul_f32_e32 v166, v228, v112
	v_mul_f32_e32 v167, v228, v113
	v_rndne_f32_e32 v164, v164
	v_rndne_f32_e32 v165, v165
	v_rndne_f32_e32 v166, v166
	v_rndne_f32_e32 v167, v167
	v_med3_f32 v164, v164, s71, v183
	v_med3_f32 v165, v165, s71, v183
	v_med3_f32 v166, v166, s71, v183
	v_med3_f32 v167, v167, s71, v183
	v_cvt_i32_f32_e32 v164, v164
	v_cvt_i32_f32_e32 v165, v165
	v_cvt_i32_f32_e32 v166, v166
	v_cvt_i32_f32_e32 v167, v167
	v_and_b32_e32 v164, 0xff, v164
	v_and_b32_e32 v165, 0xff, v165
	v_and_b32_e32 v166, 0xff, v166
	v_lshl_or_b32 v164, v165, 8, v164
	v_lshl_or_b32 v164, v166, 16, v164
	v_lshl_or_b32 v223, v167, 24, v164
	v_pk_fma_f32 v[224:225], v[110:111], v[110:111], v[224:225]
	v_pk_fma_f32 v[226:227], v[112:113], v[112:113], v[226:227]
	global_store_dwordx4 v136, v[218:221], s[86:87]
	global_store_dwordx2 v137, v[222:223], s[88:89]
	s_nop 0
	v_pk_add_f32 v[106:107], v[106:107], v[210:211]
	v_pk_add_f32 v[108:109], v[108:109], v[212:213]
	v_cvt_pk_bf16_f32 v218, v106, v107
	v_cvt_pk_bf16_f32 v219, v108, v109
	v_mul_f32_e32 v164, v228, v106
	v_mul_f32_e32 v165, v228, v107
	v_mul_f32_e32 v166, v228, v108
	v_mul_f32_e32 v167, v228, v109
	v_rndne_f32_e32 v164, v164
	v_rndne_f32_e32 v165, v165
	v_rndne_f32_e32 v166, v166
	v_rndne_f32_e32 v167, v167
	v_med3_f32 v164, v164, s71, v183
	v_med3_f32 v165, v165, s71, v183
	v_med3_f32 v166, v166, s71, v183
	v_med3_f32 v167, v167, s71, v183
	v_cvt_i32_f32_e32 v164, v164
	v_cvt_i32_f32_e32 v165, v165
	v_cvt_i32_f32_e32 v166, v166
	v_cvt_i32_f32_e32 v167, v167
	v_and_b32_e32 v164, 0xff, v164
	v_and_b32_e32 v165, 0xff, v165
	v_and_b32_e32 v166, 0xff, v166
	v_lshl_or_b32 v164, v165, 8, v164
	v_lshl_or_b32 v164, v166, 16, v164
	v_lshl_or_b32 v222, v167, 24, v164
	v_pk_fma_f32 v[224:225], v[106:107], v[106:107], v[224:225]
	v_pk_fma_f32 v[226:227], v[108:109], v[108:109], v[226:227]
	v_pk_add_f32 v[102:103], v[102:103], v[214:215]
	v_pk_add_f32 v[104:105], v[104:105], v[216:217]
	v_cvt_pk_bf16_f32 v220, v102, v103
	v_cvt_pk_bf16_f32 v221, v104, v105
	v_mul_f32_e32 v164, v228, v102
	v_mul_f32_e32 v165, v228, v103
	v_mul_f32_e32 v166, v228, v104
	v_mul_f32_e32 v167, v228, v105
	v_rndne_f32_e32 v164, v164
	v_rndne_f32_e32 v165, v165
	v_rndne_f32_e32 v166, v166
	v_rndne_f32_e32 v167, v167
	v_med3_f32 v164, v164, s71, v183
	v_med3_f32 v165, v165, s71, v183
	v_med3_f32 v166, v166, s71, v183
	v_med3_f32 v167, v167, s71, v183
	v_cvt_i32_f32_e32 v164, v164
	v_cvt_i32_f32_e32 v165, v165
	v_cvt_i32_f32_e32 v166, v166
	v_cvt_i32_f32_e32 v167, v167
	v_and_b32_e32 v164, 0xff, v164
	v_and_b32_e32 v165, 0xff, v165
	v_and_b32_e32 v166, 0xff, v166
	v_lshl_or_b32 v164, v165, 8, v164
	v_lshl_or_b32 v164, v166, 16, v164
	v_lshl_or_b32 v223, v167, 24, v164
	v_pk_fma_f32 v[224:225], v[102:103], v[102:103], v[224:225]
	v_pk_fma_f32 v[226:227], v[104:105], v[104:105], v[226:227]
	global_store_dwordx4 v136, v[218:221], s[86:87] offset:256
	global_store_dwordx2 v137, v[222:223], s[88:89] offset:128
	s_nop 0
	v_add_f32_e32 v224, v224, v225
	v_add_f32_e32 v226, v226, v227
	v_add_f32_e32 v224, v224, v226
	ds_bpermute_b32 v225, v138, v224
	s_waitcnt lgkmcnt(0)
	v_add_f32_e32 v224, v224, v225
	ds_bpermute_b32 v225, v139, v224
	s_waitcnt lgkmcnt(0)
	v_add_f32_e32 v224, v224, v225
	s_and_saveexec_b64 s[32:33], s[6:7]
	global_atomic_add_f32 v134, v224, s[16:17] offset:64
	s_or_b64 exec, exec, s[32:33]
	s_add_u32 s86, s86, 0x20000
	s_addc_u32 s87, s87, 0
	s_add_u32 s88, s88, 0x10000
	s_addc_u32 s89, s89, 0
	global_load_dword v163, v134, s[14:15] offset:192
	global_load_dwordx4 v[202:205], v135, s[84:85] nt
	global_load_dwordx4 v[206:209], v135, s[84:85] offset:16 nt
	global_load_dwordx4 v[210:213], v135, s[84:85] offset:512 nt
	global_load_dwordx4 v[214:217], v135, s[84:85] offset:528 nt
	s_add_u32 s84, s84, 0x140000
	s_addc_u32 s85, s85, 0
	s_waitcnt vmcnt(10)
	v_mul_f32_e32 v228, 0x41e1c71c, v162
	v_pk_add_f32 v[98:99], v[98:99], v[186:187]
	v_pk_add_f32 v[100:101], v[100:101], v[188:189]
	v_cvt_pk_bf16_f32 v218, v98, v99
	v_cvt_pk_bf16_f32 v219, v100, v101
	v_mul_f32_e32 v164, v228, v98
	v_mul_f32_e32 v165, v228, v99
	v_mul_f32_e32 v166, v228, v100
	v_mul_f32_e32 v167, v228, v101
	v_rndne_f32_e32 v164, v164
	v_rndne_f32_e32 v165, v165
	v_rndne_f32_e32 v166, v166
	v_rndne_f32_e32 v167, v167
	v_med3_f32 v164, v164, s71, v183
	v_med3_f32 v165, v165, s71, v183
	v_med3_f32 v166, v166, s71, v183
	v_med3_f32 v167, v167, s71, v183
	v_cvt_i32_f32_e32 v164, v164
	v_cvt_i32_f32_e32 v165, v165
	v_cvt_i32_f32_e32 v166, v166
	v_cvt_i32_f32_e32 v167, v167
	v_and_b32_e32 v164, 0xff, v164
	v_and_b32_e32 v165, 0xff, v165
	v_and_b32_e32 v166, 0xff, v166
	v_lshl_or_b32 v164, v165, 8, v164
	v_lshl_or_b32 v164, v166, 16, v164
	v_lshl_or_b32 v222, v167, 24, v164
	v_pk_mul_f32 v[224:225], v[98:99], v[98:99]
	v_pk_mul_f32 v[226:227], v[100:101], v[100:101]
	v_pk_add_f32 v[94:95], v[94:95], v[190:191]
	v_pk_add_f32 v[96:97], v[96:97], v[192:193]
	v_cvt_pk_bf16_f32 v220, v94, v95
	v_cvt_pk_bf16_f32 v221, v96, v97
	v_mul_f32_e32 v164, v228, v94
	v_mul_f32_e32 v165, v228, v95
	v_mul_f32_e32 v166, v228, v96
	v_mul_f32_e32 v167, v228, v97
	v_rndne_f32_e32 v164, v164
	v_rndne_f32_e32 v165, v165
	v_rndne_f32_e32 v166, v166
	v_rndne_f32_e32 v167, v167
	v_med3_f32 v164, v164, s71, v183
	v_med3_f32 v165, v165, s71, v183
	v_med3_f32 v166, v166, s71, v183
	v_med3_f32 v167, v167, s71, v183
	v_cvt_i32_f32_e32 v164, v164
	v_cvt_i32_f32_e32 v165, v165
	v_cvt_i32_f32_e32 v166, v166
	v_cvt_i32_f32_e32 v167, v167
	v_and_b32_e32 v164, 0xff, v164
	v_and_b32_e32 v165, 0xff, v165
	v_and_b32_e32 v166, 0xff, v166
	v_lshl_or_b32 v164, v165, 8, v164
	v_lshl_or_b32 v164, v166, 16, v164
	v_lshl_or_b32 v223, v167, 24, v164
	v_pk_fma_f32 v[224:225], v[94:95], v[94:95], v[224:225]
	v_pk_fma_f32 v[226:227], v[96:97], v[96:97], v[226:227]
	global_store_dwordx4 v136, v[218:221], s[86:87]
	global_store_dwordx2 v137, v[222:223], s[88:89]
	s_nop 0
	v_pk_add_f32 v[90:91], v[90:91], v[194:195]
	v_pk_add_f32 v[92:93], v[92:93], v[196:197]
	v_cvt_pk_bf16_f32 v218, v90, v91
	v_cvt_pk_bf16_f32 v219, v92, v93
	v_mul_f32_e32 v164, v228, v90
	v_mul_f32_e32 v165, v228, v91
	v_mul_f32_e32 v166, v228, v92
	v_mul_f32_e32 v167, v228, v93
	v_rndne_f32_e32 v164, v164
	v_rndne_f32_e32 v165, v165
	v_rndne_f32_e32 v166, v166
	v_rndne_f32_e32 v167, v167
	v_med3_f32 v164, v164, s71, v183
	v_med3_f32 v165, v165, s71, v183
	v_med3_f32 v166, v166, s71, v183
	v_med3_f32 v167, v167, s71, v183
	v_cvt_i32_f32_e32 v164, v164
	v_cvt_i32_f32_e32 v165, v165
	v_cvt_i32_f32_e32 v166, v166
	v_cvt_i32_f32_e32 v167, v167
	v_and_b32_e32 v164, 0xff, v164
	v_and_b32_e32 v165, 0xff, v165
	v_and_b32_e32 v166, 0xff, v166
	v_lshl_or_b32 v164, v165, 8, v164
	v_lshl_or_b32 v164, v166, 16, v164
	v_lshl_or_b32 v222, v167, 24, v164
	v_pk_fma_f32 v[224:225], v[90:91], v[90:91], v[224:225]
	v_pk_fma_f32 v[226:227], v[92:93], v[92:93], v[226:227]
	v_pk_add_f32 v[86:87], v[86:87], v[198:199]
	v_pk_add_f32 v[88:89], v[88:89], v[200:201]
	v_cvt_pk_bf16_f32 v220, v86, v87
	v_cvt_pk_bf16_f32 v221, v88, v89
	v_mul_f32_e32 v164, v228, v86
	v_mul_f32_e32 v165, v228, v87
	v_mul_f32_e32 v166, v228, v88
	v_mul_f32_e32 v167, v228, v89
	v_rndne_f32_e32 v164, v164
	v_rndne_f32_e32 v165, v165
	v_rndne_f32_e32 v166, v166
	v_rndne_f32_e32 v167, v167
	v_med3_f32 v164, v164, s71, v183
	v_med3_f32 v165, v165, s71, v183
	v_med3_f32 v166, v166, s71, v183
	v_med3_f32 v167, v167, s71, v183
	v_cvt_i32_f32_e32 v164, v164
	v_cvt_i32_f32_e32 v165, v165
	v_cvt_i32_f32_e32 v166, v166
	v_cvt_i32_f32_e32 v167, v167
	v_and_b32_e32 v164, 0xff, v164
	v_and_b32_e32 v165, 0xff, v165
	v_and_b32_e32 v166, 0xff, v166
	v_lshl_or_b32 v164, v165, 8, v164
	v_lshl_or_b32 v164, v166, 16, v164
	v_lshl_or_b32 v223, v167, 24, v164
	v_pk_fma_f32 v[224:225], v[86:87], v[86:87], v[224:225]
	v_pk_fma_f32 v[226:227], v[88:89], v[88:89], v[226:227]
	global_store_dwordx4 v136, v[218:221], s[86:87] offset:256
	global_store_dwordx2 v137, v[222:223], s[88:89] offset:128
	s_nop 0
	v_add_f32_e32 v224, v224, v225
	v_add_f32_e32 v226, v226, v227
	v_add_f32_e32 v224, v224, v226
	ds_bpermute_b32 v225, v138, v224
	s_waitcnt lgkmcnt(0)
	v_add_f32_e32 v224, v224, v225
	ds_bpermute_b32 v225, v139, v224
	s_waitcnt lgkmcnt(0)
	v_add_f32_e32 v224, v224, v225
	s_and_saveexec_b64 s[32:33], s[6:7]
	global_atomic_add_f32 v134, v224, s[16:17] offset:128
	s_or_b64 exec, exec, s[32:33]
	s_add_u32 s86, s86, 0x20000
	s_addc_u32 s87, s87, 0
	s_add_u32 s88, s88, 0x10000
	s_addc_u32 s89, s89, 0
	global_load_dword v162, v134, s[14:15] offset:512
	global_load_dwordx4 v[186:189], v135, s[84:85] nt
	global_load_dwordx4 v[190:193], v135, s[84:85] offset:16 nt
	global_load_dwordx4 v[194:197], v135, s[84:85] offset:512 nt
	global_load_dwordx4 v[198:201], v135, s[84:85] offset:528 nt
	s_add_u32 s84, s84, 0x40000
	s_addc_u32 s85, s85, 0
	s_waitcnt vmcnt(10)
	v_mul_f32_e32 v228, 0x41e1c71c, v163
	v_pk_add_f32 v[82:83], v[82:83], v[202:203]
	v_pk_add_f32 v[84:85], v[84:85], v[204:205]
	v_cvt_pk_bf16_f32 v218, v82, v83
	v_cvt_pk_bf16_f32 v219, v84, v85
	v_mul_f32_e32 v164, v228, v82
	v_mul_f32_e32 v165, v228, v83
	v_mul_f32_e32 v166, v228, v84
	v_mul_f32_e32 v167, v228, v85
	v_rndne_f32_e32 v164, v164
	v_rndne_f32_e32 v165, v165
	v_rndne_f32_e32 v166, v166
	v_rndne_f32_e32 v167, v167
	v_med3_f32 v164, v164, s71, v183
	v_med3_f32 v165, v165, s71, v183
	v_med3_f32 v166, v166, s71, v183
	v_med3_f32 v167, v167, s71, v183
	v_cvt_i32_f32_e32 v164, v164
	v_cvt_i32_f32_e32 v165, v165
	v_cvt_i32_f32_e32 v166, v166
	v_cvt_i32_f32_e32 v167, v167
	v_and_b32_e32 v164, 0xff, v164
	v_and_b32_e32 v165, 0xff, v165
	v_and_b32_e32 v166, 0xff, v166
	v_lshl_or_b32 v164, v165, 8, v164
	v_lshl_or_b32 v164, v166, 16, v164
	v_lshl_or_b32 v222, v167, 24, v164
	v_pk_mul_f32 v[224:225], v[82:83], v[82:83]
	v_pk_mul_f32 v[226:227], v[84:85], v[84:85]
	v_pk_add_f32 v[78:79], v[78:79], v[206:207]
	v_pk_add_f32 v[80:81], v[80:81], v[208:209]
	v_cvt_pk_bf16_f32 v220, v78, v79
	v_cvt_pk_bf16_f32 v221, v80, v81
	v_mul_f32_e32 v164, v228, v78
	v_mul_f32_e32 v165, v228, v79
	v_mul_f32_e32 v166, v228, v80
	v_mul_f32_e32 v167, v228, v81
	v_rndne_f32_e32 v164, v164
	v_rndne_f32_e32 v165, v165
	v_rndne_f32_e32 v166, v166
	v_rndne_f32_e32 v167, v167
	v_med3_f32 v164, v164, s71, v183
	v_med3_f32 v165, v165, s71, v183
	v_med3_f32 v166, v166, s71, v183
	v_med3_f32 v167, v167, s71, v183
	v_cvt_i32_f32_e32 v164, v164
	v_cvt_i32_f32_e32 v165, v165
	v_cvt_i32_f32_e32 v166, v166
	v_cvt_i32_f32_e32 v167, v167
	v_and_b32_e32 v164, 0xff, v164
	v_and_b32_e32 v165, 0xff, v165
	v_and_b32_e32 v166, 0xff, v166
	v_lshl_or_b32 v164, v165, 8, v164
	v_lshl_or_b32 v164, v166, 16, v164
	v_lshl_or_b32 v223, v167, 24, v164
	v_pk_fma_f32 v[224:225], v[78:79], v[78:79], v[224:225]
	v_pk_fma_f32 v[226:227], v[80:81], v[80:81], v[226:227]
	global_store_dwordx4 v136, v[218:221], s[86:87]
	global_store_dwordx2 v137, v[222:223], s[88:89]
	s_nop 0
	v_pk_add_f32 v[74:75], v[74:75], v[210:211]
	v_pk_add_f32 v[76:77], v[76:77], v[212:213]
	v_cvt_pk_bf16_f32 v218, v74, v75
	v_cvt_pk_bf16_f32 v219, v76, v77
	v_mul_f32_e32 v164, v228, v74
	v_mul_f32_e32 v165, v228, v75
	v_mul_f32_e32 v166, v228, v76
	v_mul_f32_e32 v167, v228, v77
	v_rndne_f32_e32 v164, v164
	v_rndne_f32_e32 v165, v165
	v_rndne_f32_e32 v166, v166
	v_rndne_f32_e32 v167, v167
	v_med3_f32 v164, v164, s71, v183
	v_med3_f32 v165, v165, s71, v183
	v_med3_f32 v166, v166, s71, v183
	v_med3_f32 v167, v167, s71, v183
	v_cvt_i32_f32_e32 v164, v164
	v_cvt_i32_f32_e32 v165, v165
	v_cvt_i32_f32_e32 v166, v166
	v_cvt_i32_f32_e32 v167, v167
	v_and_b32_e32 v164, 0xff, v164
	v_and_b32_e32 v165, 0xff, v165
	v_and_b32_e32 v166, 0xff, v166
	v_lshl_or_b32 v164, v165, 8, v164
	v_lshl_or_b32 v164, v166, 16, v164
	v_lshl_or_b32 v222, v167, 24, v164
	v_pk_fma_f32 v[224:225], v[74:75], v[74:75], v[224:225]
	v_pk_fma_f32 v[226:227], v[76:77], v[76:77], v[226:227]
	v_pk_add_f32 v[70:71], v[70:71], v[214:215]
	v_pk_add_f32 v[72:73], v[72:73], v[216:217]
	v_cvt_pk_bf16_f32 v220, v70, v71
	v_cvt_pk_bf16_f32 v221, v72, v73
	v_mul_f32_e32 v164, v228, v70
	v_mul_f32_e32 v165, v228, v71
	v_mul_f32_e32 v166, v228, v72
	v_mul_f32_e32 v167, v228, v73
	v_rndne_f32_e32 v164, v164
	v_rndne_f32_e32 v165, v165
	v_rndne_f32_e32 v166, v166
	v_rndne_f32_e32 v167, v167
	v_med3_f32 v164, v164, s71, v183
	v_med3_f32 v165, v165, s71, v183
	v_med3_f32 v166, v166, s71, v183
	v_med3_f32 v167, v167, s71, v183
	v_cvt_i32_f32_e32 v164, v164
	v_cvt_i32_f32_e32 v165, v165
	v_cvt_i32_f32_e32 v166, v166
	v_cvt_i32_f32_e32 v167, v167
	v_and_b32_e32 v164, 0xff, v164
	v_and_b32_e32 v165, 0xff, v165
	v_and_b32_e32 v166, 0xff, v166
	v_lshl_or_b32 v164, v165, 8, v164
	v_lshl_or_b32 v164, v166, 16, v164
	v_lshl_or_b32 v223, v167, 24, v164
	v_pk_fma_f32 v[224:225], v[70:71], v[70:71], v[224:225]
	v_pk_fma_f32 v[226:227], v[72:73], v[72:73], v[226:227]
	global_store_dwordx4 v136, v[218:221], s[86:87] offset:256
	global_store_dwordx2 v137, v[222:223], s[88:89] offset:128
	s_nop 0
	v_add_f32_e32 v224, v224, v225
	v_add_f32_e32 v226, v226, v227
	v_add_f32_e32 v224, v224, v226
	ds_bpermute_b32 v225, v138, v224
	s_waitcnt lgkmcnt(0)
	v_add_f32_e32 v224, v224, v225
	ds_bpermute_b32 v225, v139, v224
	s_waitcnt lgkmcnt(0)
	v_add_f32_e32 v224, v224, v225
	s_and_saveexec_b64 s[32:33], s[6:7]
	global_atomic_add_f32 v134, v224, s[16:17] offset:192
	s_or_b64 exec, exec, s[32:33]
	s_add_u32 s86, s86, 0xa0000
	s_addc_u32 s87, s87, 0
	s_add_u32 s88, s88, 0x50000
	s_addc_u32 s89, s89, 0
	global_load_dword v163, v134, s[14:15] offset:576
	global_load_dwordx4 v[202:205], v135, s[84:85] nt
	global_load_dwordx4 v[206:209], v135, s[84:85] offset:16 nt
	global_load_dwordx4 v[210:213], v135, s[84:85] offset:512 nt
	global_load_dwordx4 v[214:217], v135, s[84:85] offset:528 nt
	s_add_u32 s84, s84, 0x40000
	s_addc_u32 s85, s85, 0
	s_waitcnt vmcnt(10)
; __device__ __forceinline__ u32x4 pack8(const f32x4 a, const f32x4 b) { u32x4 w; w.x = cvt_pk_bf16(a[0], a[1]); w.y = cvt_pk_bf16(a[2], a[3]); w.z = cvt_pk_bf16(b[0], b[1]); w.w = cvt_pk_bf16(b[2], b[3]); return w; }
;     __device__ __forceinline__ void operator()(const f32x4 (&acc)[2][2][4][2], const pg8::Unit& u, int wr, int wc, int fr, int fq) const {
;     ...
;                 for (int mm = 0; mm < 2; ++mm) { const int row = row0 + ai * 128 + (2 * mp + mm) * 16; iqv[mm] = rs0[row];
; #pragma unroll
;                     for (int bj = 0; bj < 2; ++bj) { const size_t off = (size_t)row * DM + col0 + bj * 128; xr[mm][bj][0] = *(const f32x4*)(x + off); xr[mm][bj][1] = *(const f32x4*)(x + off + 4); } }
; #pragma unroll
;                 for (int mm = 0; mm < 2; ++mm) { const int m = 2 * mp + mm, row = row0 + ai * 128 + m * 16; float ss = 0.f; const float iq = (127.f / QCLIP) * iqv[mm];
; #pragma unroll
;                     for (int bj = 0; bj < 2; ++bj) { const size_t off = (size_t)row * DM + col0 + bj * 128;
;                         const f32x4 h0 = xr[mm][bj][0] + acc[ai][bj][m][0], h1 = xr[mm][bj][1] + acc[ai][bj][m][1];
;                         *(u32x4*)(HB + off) = pack8(h0, h1);
;                         { f32x4 q0, q1;
; #pragma unroll
;                           for (int ee = 0; ee < 4; ++ee) { q0[ee] = fminf(fmaxf(rintf(h0[ee] * iq), -127.f), 127.f); q1[ee] = fminf(fmaxf(rintf(h1[ee] * iq), -127.f), 127.f); }
;                           *(u32x2*)(HQ + off) = pack8_i8(q0, q1); }
;                         ss += (h0[0] * h0[0] + h0[1] * h0[1]) + (h0[2] * h0[2] + h0[3] * h0[3]) + (h1[0] * h1[0] + h1[1] * h1[1]) + (h1[2] * h1[2] + h1[3] * h1[3]); }
;                     ss += __shfl_xor(ss, 16); ss += __shfl_xor(ss, 32);
;                     if (fq == 0) unsafeAtomicAdd(rss1 + row, ss); }
	v_mul_f32_e32 v228, 0x41e1c71c, v162
	v_pk_add_f32 v[66:67], v[66:67], v[186:187]
	v_pk_add_f32 v[68:69], v[68:69], v[188:189]
	v_cvt_pk_bf16_f32 v218, v66, v67
	v_cvt_pk_bf16_f32 v219, v68, v69
	v_mul_f32_e32 v164, v228, v66
	v_mul_f32_e32 v165, v228, v67
	v_mul_f32_e32 v166, v228, v68
	v_mul_f32_e32 v167, v228, v69
	v_rndne_f32_e32 v164, v164
	v_rndne_f32_e32 v165, v165
	v_rndne_f32_e32 v166, v166
	v_rndne_f32_e32 v167, v167
	v_med3_f32 v164, v164, s71, v183
	v_med3_f32 v165, v165, s71, v183
	v_med3_f32 v166, v166, s71, v183
	v_med3_f32 v167, v167, s71, v183
	v_cvt_i32_f32_e32 v164, v164
	v_cvt_i32_f32_e32 v165, v165
	v_cvt_i32_f32_e32 v166, v166
	v_cvt_i32_f32_e32 v167, v167
	v_and_b32_e32 v164, 0xff, v164
	v_and_b32_e32 v165, 0xff, v165
	v_and_b32_e32 v166, 0xff, v166
	v_lshl_or_b32 v164, v165, 8, v164
	v_lshl_or_b32 v164, v166, 16, v164
	v_lshl_or_b32 v222, v167, 24, v164
	v_pk_mul_f32 v[224:225], v[66:67], v[66:67]
	v_pk_mul_f32 v[226:227], v[68:69], v[68:69]
	v_pk_add_f32 v[62:63], v[62:63], v[190:191]
	v_pk_add_f32 v[64:65], v[64:65], v[192:193]
	v_cvt_pk_bf16_f32 v220, v62, v63
	v_cvt_pk_bf16_f32 v221, v64, v65
	v_mul_f32_e32 v164, v228, v62
	v_mul_f32_e32 v165, v228, v63
	v_mul_f32_e32 v166, v228, v64
	v_mul_f32_e32 v167, v228, v65
	v_rndne_f32_e32 v164, v164
	v_rndne_f32_e32 v165, v165
	v_rndne_f32_e32 v166, v166
	v_rndne_f32_e32 v167, v167
	v_med3_f32 v164, v164, s71, v183
	v_med3_f32 v165, v165, s71, v183
	v_med3_f32 v166, v166, s71, v183
	v_med3_f32 v167, v167, s71, v183
	v_cvt_i32_f32_e32 v164, v164
	v_cvt_i32_f32_e32 v165, v165
	v_cvt_i32_f32_e32 v166, v166
	v_cvt_i32_f32_e32 v167, v167
	v_and_b32_e32 v164, 0xff, v164
	v_and_b32_e32 v165, 0xff, v165
	v_and_b32_e32 v166, 0xff, v166
	v_lshl_or_b32 v164, v165, 8, v164
	v_lshl_or_b32 v164, v166, 16, v164
	v_lshl_or_b32 v223, v167, 24, v164
	v_pk_fma_f32 v[224:225], v[62:63], v[62:63], v[224:225]
	v_pk_fma_f32 v[226:227], v[64:65], v[64:65], v[226:227]
	global_store_dwordx4 v136, v[218:221], s[86:87]
	global_store_dwordx2 v137, v[222:223], s[88:89]
	s_nop 0
	v_pk_add_f32 v[58:59], v[58:59], v[194:195]
	v_pk_add_f32 v[60:61], v[60:61], v[196:197]
	v_cvt_pk_bf16_f32 v218, v58, v59
	v_cvt_pk_bf16_f32 v219, v60, v61
	v_mul_f32_e32 v164, v228, v58
	v_mul_f32_e32 v165, v228, v59
	v_mul_f32_e32 v166, v228, v60
	v_mul_f32_e32 v167, v228, v61
	v_rndne_f32_e32 v164, v164
	v_rndne_f32_e32 v165, v165
	v_rndne_f32_e32 v166, v166
	v_rndne_f32_e32 v167, v167
	v_med3_f32 v164, v164, s71, v183
	v_med3_f32 v165, v165, s71, v183
	v_med3_f32 v166, v166, s71, v183
	v_med3_f32 v167, v167, s71, v183
	v_cvt_i32_f32_e32 v164, v164
	v_cvt_i32_f32_e32 v165, v165
	v_cvt_i32_f32_e32 v166, v166
	v_cvt_i32_f32_e32 v167, v167
	v_and_b32_e32 v164, 0xff, v164
	v_and_b32_e32 v165, 0xff, v165
	v_and_b32_e32 v166, 0xff, v166
	v_lshl_or_b32 v164, v165, 8, v164
	v_lshl_or_b32 v164, v166, 16, v164
	v_lshl_or_b32 v222, v167, 24, v164
	v_pk_fma_f32 v[224:225], v[58:59], v[58:59], v[224:225]
	v_pk_fma_f32 v[226:227], v[60:61], v[60:61], v[226:227]
	v_pk_add_f32 v[54:55], v[54:55], v[198:199]
	v_pk_add_f32 v[56:57], v[56:57], v[200:201]
	v_cvt_pk_bf16_f32 v220, v54, v55
	v_cvt_pk_bf16_f32 v221, v56, v57
	v_mul_f32_e32 v164, v228, v54
	v_mul_f32_e32 v165, v228, v55
	v_mul_f32_e32 v166, v228, v56
	v_mul_f32_e32 v167, v228, v57
	v_rndne_f32_e32 v164, v164
	v_rndne_f32_e32 v165, v165
	v_rndne_f32_e32 v166, v166
	v_rndne_f32_e32 v167, v167
	v_med3_f32 v164, v164, s71, v183
	v_med3_f32 v165, v165, s71, v183
	v_med3_f32 v166, v166, s71, v183
	v_med3_f32 v167, v167, s71, v183
	v_cvt_i32_f32_e32 v164, v164
	v_cvt_i32_f32_e32 v165, v165
	v_cvt_i32_f32_e32 v166, v166
	v_cvt_i32_f32_e32 v167, v167
	v_and_b32_e32 v164, 0xff, v164
	v_and_b32_e32 v165, 0xff, v165
	v_and_b32_e32 v166, 0xff, v166
	v_lshl_or_b32 v164, v165, 8, v164
	v_lshl_or_b32 v164, v166, 16, v164
	v_lshl_or_b32 v223, v167, 24, v164
	v_pk_fma_f32 v[224:225], v[54:55], v[54:55], v[224:225]
	v_pk_fma_f32 v[226:227], v[56:57], v[56:57], v[226:227]
	global_store_dwordx4 v136, v[218:221], s[86:87] offset:256
	global_store_dwordx2 v137, v[222:223], s[88:89] offset:128
	s_nop 0
	v_add_f32_e32 v224, v224, v225
	v_add_f32_e32 v226, v226, v227
	v_add_f32_e32 v224, v224, v226
	ds_bpermute_b32 v225, v138, v224
	s_waitcnt lgkmcnt(0)
	v_add_f32_e32 v224, v224, v225
	ds_bpermute_b32 v225, v139, v224
	s_waitcnt lgkmcnt(0)
	v_add_f32_e32 v224, v224, v225
	s_and_saveexec_b64 s[32:33], s[6:7]
	global_atomic_add_f32 v134, v224, s[16:17] offset:512
	s_or_b64 exec, exec, s[32:33]
	s_add_u32 s86, s86, 0x20000
	s_addc_u32 s87, s87, 0
	s_add_u32 s88, s88, 0x10000
	s_addc_u32 s89, s89, 0
	global_load_dword v162, v134, s[14:15] offset:640
	global_load_dwordx4 v[186:189], v135, s[84:85] nt
	global_load_dwordx4 v[190:193], v135, s[84:85] offset:16 nt
	global_load_dwordx4 v[194:197], v135, s[84:85] offset:512 nt
	global_load_dwordx4 v[198:201], v135, s[84:85] offset:528 nt
	s_add_u32 s84, s84, 0x40000
	s_addc_u32 s85, s85, 0
	s_waitcnt vmcnt(10)
; __device__ __forceinline__ u32x4 pack8(const f32x4 a, const f32x4 b) { u32x4 w; w.x = cvt_pk_bf16(a[0], a[1]); w.y = cvt_pk_bf16(a[2], a[3]); w.z = cvt_pk_bf16(b[0], b[1]); w.w = cvt_pk_bf16(b[2], b[3]); return w; }
;     __device__ __forceinline__ void operator()(const f32x4 (&acc)[2][2][4][2], const pg8::Unit& u, int wr, int wc, int fr, int fq) const {
;     ...
;                 for (int mm = 0; mm < 2; ++mm) { const int row = row0 + ai * 128 + (2 * mp + mm) * 16; iqv[mm] = rs0[row];
; #pragma unroll
;                     for (int bj = 0; bj < 2; ++bj) { const size_t off = (size_t)row * DM + col0 + bj * 128; xr[mm][bj][0] = *(const f32x4*)(x + off); xr[mm][bj][1] = *(const f32x4*)(x + off + 4); } }
; #pragma unroll
;                 for (int mm = 0; mm < 2; ++mm) { const int m = 2 * mp + mm, row = row0 + ai * 128 + m * 16; float ss = 0.f; const float iq = (127.f / QCLIP) * iqv[mm];
; #pragma unroll
;                     for (int bj = 0; bj < 2; ++bj) { const size_t off = (size_t)row * DM + col0 + bj * 128;
;                         const f32x4 h0 = xr[mm][bj][0] + acc[ai][bj][m][0], h1 = xr[mm][bj][1] + acc[ai][bj][m][1];
;                         *(u32x4*)(HB + off) = pack8(h0, h1);
;                         { f32x4 q0, q1;
; #pragma unroll
;                           for (int ee = 0; ee < 4; ++ee) { q0[ee] = fminf(fmaxf(rintf(h0[ee] * iq), -127.f), 127.f); q1[ee] = fminf(fmaxf(rintf(h1[ee] * iq), -127.f), 127.f); }
;                           *(u32x2*)(HQ + off) = pack8_i8(q0, q1); }
;                         ss += (h0[0] * h0[0] + h0[1] * h0[1]) + (h0[2] * h0[2] + h0[3] * h0[3]) + (h1[0] * h1[0] + h1[1] * h1[1]) + (h1[2] * h1[2] + h1[3] * h1[3]); }
;                     ss += __shfl_xor(ss, 16); ss += __shfl_xor(ss, 32);
;                     if (fq == 0) unsafeAtomicAdd(rss1 + row, ss); }
	v_mul_f32_e32 v228, 0x41e1c71c, v163
	v_pk_add_f32 v[50:51], v[50:51], v[202:203]
	v_pk_add_f32 v[52:53], v[52:53], v[204:205]
	v_cvt_pk_bf16_f32 v218, v50, v51
	v_cvt_pk_bf16_f32 v219, v52, v53
	v_mul_f32_e32 v164, v228, v50
	v_mul_f32_e32 v165, v228, v51
	v_mul_f32_e32 v166, v228, v52
	v_mul_f32_e32 v167, v228, v53
	v_rndne_f32_e32 v164, v164
	v_rndne_f32_e32 v165, v165
	v_rndne_f32_e32 v166, v166
	v_rndne_f32_e32 v167, v167
	v_med3_f32 v164, v164, s71, v183
	v_med3_f32 v165, v165, s71, v183
	v_med3_f32 v166, v166, s71, v183
	v_med3_f32 v167, v167, s71, v183
	v_cvt_i32_f32_e32 v164, v164
	v_cvt_i32_f32_e32 v165, v165
	v_cvt_i32_f32_e32 v166, v166
	v_cvt_i32_f32_e32 v167, v167
	v_and_b32_e32 v164, 0xff, v164
	v_and_b32_e32 v165, 0xff, v165
	v_and_b32_e32 v166, 0xff, v166
	v_lshl_or_b32 v164, v165, 8, v164
	v_lshl_or_b32 v164, v166, 16, v164
	v_lshl_or_b32 v222, v167, 24, v164
	v_pk_mul_f32 v[224:225], v[50:51], v[50:51]
	v_pk_mul_f32 v[226:227], v[52:53], v[52:53]
	v_pk_add_f32 v[46:47], v[46:47], v[206:207]
	v_pk_add_f32 v[48:49], v[48:49], v[208:209]
	v_cvt_pk_bf16_f32 v220, v46, v47
	v_cvt_pk_bf16_f32 v221, v48, v49
	v_mul_f32_e32 v164, v228, v46
	v_mul_f32_e32 v165, v228, v47
	v_mul_f32_e32 v166, v228, v48
	v_mul_f32_e32 v167, v228, v49
	v_rndne_f32_e32 v164, v164
	v_rndne_f32_e32 v165, v165
	v_rndne_f32_e32 v166, v166
	v_rndne_f32_e32 v167, v167
	v_med3_f32 v164, v164, s71, v183
	v_med3_f32 v165, v165, s71, v183
	v_med3_f32 v166, v166, s71, v183
	v_med3_f32 v167, v167, s71, v183
	v_cvt_i32_f32_e32 v164, v164
	v_cvt_i32_f32_e32 v165, v165
	v_cvt_i32_f32_e32 v166, v166
	v_cvt_i32_f32_e32 v167, v167
	v_and_b32_e32 v164, 0xff, v164
	v_and_b32_e32 v165, 0xff, v165
	v_and_b32_e32 v166, 0xff, v166
	v_lshl_or_b32 v164, v165, 8, v164
	v_lshl_or_b32 v164, v166, 16, v164
	v_lshl_or_b32 v223, v167, 24, v164
	v_pk_fma_f32 v[224:225], v[46:47], v[46:47], v[224:225]
	v_pk_fma_f32 v[226:227], v[48:49], v[48:49], v[226:227]
	global_store_dwordx4 v136, v[218:221], s[86:87]
	global_store_dwordx2 v137, v[222:223], s[88:89]
	s_nop 0
	v_pk_add_f32 v[42:43], v[42:43], v[210:211]
	v_pk_add_f32 v[44:45], v[44:45], v[212:213]
	v_cvt_pk_bf16_f32 v218, v42, v43
	v_cvt_pk_bf16_f32 v219, v44, v45
	v_mul_f32_e32 v164, v228, v42
	v_mul_f32_e32 v165, v228, v43
	v_mul_f32_e32 v166, v228, v44
	v_mul_f32_e32 v167, v228, v45
	v_rndne_f32_e32 v164, v164
	v_rndne_f32_e32 v165, v165
	v_rndne_f32_e32 v166, v166
	v_rndne_f32_e32 v167, v167
	v_med3_f32 v164, v164, s71, v183
	v_med3_f32 v165, v165, s71, v183
	v_med3_f32 v166, v166, s71, v183
	v_med3_f32 v167, v167, s71, v183
	v_cvt_i32_f32_e32 v164, v164
	v_cvt_i32_f32_e32 v165, v165
	v_cvt_i32_f32_e32 v166, v166
	v_cvt_i32_f32_e32 v167, v167
	v_and_b32_e32 v164, 0xff, v164
	v_and_b32_e32 v165, 0xff, v165
	v_and_b32_e32 v166, 0xff, v166
	v_lshl_or_b32 v164, v165, 8, v164
	v_lshl_or_b32 v164, v166, 16, v164
	v_lshl_or_b32 v222, v167, 24, v164
	v_pk_fma_f32 v[224:225], v[42:43], v[42:43], v[224:225]
	v_pk_fma_f32 v[226:227], v[44:45], v[44:45], v[226:227]
	v_pk_add_f32 v[38:39], v[38:39], v[214:215]
	v_pk_add_f32 v[40:41], v[40:41], v[216:217]
	v_cvt_pk_bf16_f32 v220, v38, v39
	v_cvt_pk_bf16_f32 v221, v40, v41
	v_mul_f32_e32 v164, v228, v38
	v_mul_f32_e32 v165, v228, v39
	v_mul_f32_e32 v166, v228, v40
	v_mul_f32_e32 v167, v228, v41
	v_rndne_f32_e32 v164, v164
	v_rndne_f32_e32 v165, v165
	v_rndne_f32_e32 v166, v166
	v_rndne_f32_e32 v167, v167
	v_med3_f32 v164, v164, s71, v183
	v_med3_f32 v165, v165, s71, v183
	v_med3_f32 v166, v166, s71, v183
	v_med3_f32 v167, v167, s71, v183
	v_cvt_i32_f32_e32 v164, v164
	v_cvt_i32_f32_e32 v165, v165
	v_cvt_i32_f32_e32 v166, v166
	v_cvt_i32_f32_e32 v167, v167
	v_and_b32_e32 v164, 0xff, v164
	v_and_b32_e32 v165, 0xff, v165
	v_and_b32_e32 v166, 0xff, v166
	v_lshl_or_b32 v164, v165, 8, v164
	v_lshl_or_b32 v164, v166, 16, v164
	v_lshl_or_b32 v223, v167, 24, v164
	v_pk_fma_f32 v[224:225], v[38:39], v[38:39], v[224:225]
	v_pk_fma_f32 v[226:227], v[40:41], v[40:41], v[226:227]
	global_store_dwordx4 v136, v[218:221], s[86:87] offset:256
	global_store_dwordx2 v137, v[222:223], s[88:89] offset:128
	s_nop 0
	v_add_f32_e32 v224, v224, v225
	v_add_f32_e32 v226, v226, v227
	v_add_f32_e32 v224, v224, v226
	ds_bpermute_b32 v225, v138, v224
	s_waitcnt lgkmcnt(0)
	v_add_f32_e32 v224, v224, v225
	ds_bpermute_b32 v225, v139, v224
	s_waitcnt lgkmcnt(0)
	v_add_f32_e32 v224, v224, v225
	s_and_saveexec_b64 s[32:33], s[6:7]
	global_atomic_add_f32 v134, v224, s[16:17] offset:576
	s_or_b64 exec, exec, s[32:33]
	s_add_u32 s86, s86, 0x20000
	s_addc_u32 s87, s87, 0
	s_add_u32 s88, s88, 0x10000
	s_addc_u32 s89, s89, 0
	global_load_dword v163, v134, s[14:15] offset:704
	global_load_dwordx4 v[202:205], v135, s[84:85] nt
	global_load_dwordx4 v[206:209], v135, s[84:85] offset:16 nt
	global_load_dwordx4 v[210:213], v135, s[84:85] offset:512 nt
	global_load_dwordx4 v[214:217], v135, s[84:85] offset:528 nt
	s_waitcnt vmcnt(10)
; __device__ __forceinline__ u32x4 pack8(const f32x4 a, const f32x4 b) { u32x4 w; w.x = cvt_pk_bf16(a[0], a[1]); w.y = cvt_pk_bf16(a[2], a[3]); w.z = cvt_pk_bf16(b[0], b[1]); w.w = cvt_pk_bf16(b[2], b[3]); return w; }
;     __device__ __forceinline__ void operator()(const f32x4 (&acc)[2][2][4][2], const pg8::Unit& u, int wr, int wc, int fr, int fq) const {
;     ...
;                 for (int mm = 0; mm < 2; ++mm) { const int m = 2 * mp + mm, row = row0 + ai * 128 + m * 16; float ss = 0.f; const float iq = (127.f / QCLIP) * iqv[mm];
; #pragma unroll
;                     for (int bj = 0; bj < 2; ++bj) { const size_t off = (size_t)row * DM + col0 + bj * 128;
;                         const f32x4 h0 = xr[mm][bj][0] + acc[ai][bj][m][0], h1 = xr[mm][bj][1] + acc[ai][bj][m][1];
;                         *(u32x4*)(HB + off) = pack8(h0, h1);
;                         { f32x4 q0, q1;
; #pragma unroll
;                           for (int ee = 0; ee < 4; ++ee) { q0[ee] = fminf(fmaxf(rintf(h0[ee] * iq), -127.f), 127.f); q1[ee] = fminf(fmaxf(rintf(h1[ee] * iq), -127.f), 127.f); }
;                           *(u32x2*)(HQ + off) = pack8_i8(q0, q1); }
;                         ss += (h0[0] * h0[0] + h0[1] * h0[1]) + (h0[2] * h0[2] + h0[3] * h0[3]) + (h1[0] * h1[0] + h1[1] * h1[1]) + (h1[2] * h1[2] + h1[3] * h1[3]); }
;                     ss += __shfl_xor(ss, 16); ss += __shfl_xor(ss, 32);
;                     if (fq == 0) unsafeAtomicAdd(rss1 + row, ss); }
	v_mul_f32_e32 v228, 0x41e1c71c, v162
	v_pk_add_f32 v[34:35], v[34:35], v[186:187]
	v_pk_add_f32 v[36:37], v[36:37], v[188:189]
	v_cvt_pk_bf16_f32 v218, v34, v35
	v_cvt_pk_bf16_f32 v219, v36, v37
	v_mul_f32_e32 v164, v228, v34
	v_mul_f32_e32 v165, v228, v35
	v_mul_f32_e32 v166, v228, v36
	v_mul_f32_e32 v167, v228, v37
	v_rndne_f32_e32 v164, v164
	v_rndne_f32_e32 v165, v165
	v_rndne_f32_e32 v166, v166
	v_rndne_f32_e32 v167, v167
	v_med3_f32 v164, v164, s71, v183
	v_med3_f32 v165, v165, s71, v183
	v_med3_f32 v166, v166, s71, v183
	v_med3_f32 v167, v167, s71, v183
	v_cvt_i32_f32_e32 v164, v164
	v_cvt_i32_f32_e32 v165, v165
	v_cvt_i32_f32_e32 v166, v166
	v_cvt_i32_f32_e32 v167, v167
	v_and_b32_e32 v164, 0xff, v164
	v_and_b32_e32 v165, 0xff, v165
	v_and_b32_e32 v166, 0xff, v166
	v_lshl_or_b32 v164, v165, 8, v164
	v_lshl_or_b32 v164, v166, 16, v164
	v_lshl_or_b32 v222, v167, 24, v164
	v_pk_mul_f32 v[224:225], v[34:35], v[34:35]
	v_pk_mul_f32 v[226:227], v[36:37], v[36:37]
	v_pk_add_f32 v[30:31], v[30:31], v[190:191]
	v_pk_add_f32 v[32:33], v[32:33], v[192:193]
	v_cvt_pk_bf16_f32 v220, v30, v31
	v_cvt_pk_bf16_f32 v221, v32, v33
	v_mul_f32_e32 v164, v228, v30
	v_mul_f32_e32 v165, v228, v31
	v_mul_f32_e32 v166, v228, v32
	v_mul_f32_e32 v167, v228, v33
	v_rndne_f32_e32 v164, v164
	v_rndne_f32_e32 v165, v165
	v_rndne_f32_e32 v166, v166
	v_rndne_f32_e32 v167, v167
	v_med3_f32 v164, v164, s71, v183
	v_med3_f32 v165, v165, s71, v183
	v_med3_f32 v166, v166, s71, v183
	v_med3_f32 v167, v167, s71, v183
	v_cvt_i32_f32_e32 v164, v164
	v_cvt_i32_f32_e32 v165, v165
	v_cvt_i32_f32_e32 v166, v166
	v_cvt_i32_f32_e32 v167, v167
	v_and_b32_e32 v164, 0xff, v164
	v_and_b32_e32 v165, 0xff, v165
	v_and_b32_e32 v166, 0xff, v166
	v_lshl_or_b32 v164, v165, 8, v164
	v_lshl_or_b32 v164, v166, 16, v164
	v_lshl_or_b32 v223, v167, 24, v164
	v_pk_fma_f32 v[224:225], v[30:31], v[30:31], v[224:225]
	v_pk_fma_f32 v[226:227], v[32:33], v[32:33], v[226:227]
	global_store_dwordx4 v136, v[218:221], s[86:87]
	global_store_dwordx2 v137, v[222:223], s[88:89]
	s_nop 0
	v_pk_add_f32 v[26:27], v[26:27], v[194:195]
	v_pk_add_f32 v[28:29], v[28:29], v[196:197]
	v_cvt_pk_bf16_f32 v218, v26, v27
	v_cvt_pk_bf16_f32 v219, v28, v29
	v_mul_f32_e32 v164, v228, v26
	v_mul_f32_e32 v165, v228, v27
	v_mul_f32_e32 v166, v228, v28
	v_mul_f32_e32 v167, v228, v29
	v_rndne_f32_e32 v164, v164
	v_rndne_f32_e32 v165, v165
	v_rndne_f32_e32 v166, v166
	v_rndne_f32_e32 v167, v167
	v_med3_f32 v164, v164, s71, v183
	v_med3_f32 v165, v165, s71, v183
	v_med3_f32 v166, v166, s71, v183
	v_med3_f32 v167, v167, s71, v183
	v_cvt_i32_f32_e32 v164, v164
	v_cvt_i32_f32_e32 v165, v165
	v_cvt_i32_f32_e32 v166, v166
	v_cvt_i32_f32_e32 v167, v167
	v_and_b32_e32 v164, 0xff, v164
	v_and_b32_e32 v165, 0xff, v165
	v_and_b32_e32 v166, 0xff, v166
	v_lshl_or_b32 v164, v165, 8, v164
	v_lshl_or_b32 v164, v166, 16, v164
	v_lshl_or_b32 v222, v167, 24, v164
	v_pk_fma_f32 v[224:225], v[26:27], v[26:27], v[224:225]
	v_pk_fma_f32 v[226:227], v[28:29], v[28:29], v[226:227]
	v_pk_add_f32 v[22:23], v[22:23], v[198:199]
	v_pk_add_f32 v[24:25], v[24:25], v[200:201]
	v_cvt_pk_bf16_f32 v220, v22, v23
	v_cvt_pk_bf16_f32 v221, v24, v25
	v_mul_f32_e32 v164, v228, v22
	v_mul_f32_e32 v165, v228, v23
	v_mul_f32_e32 v166, v228, v24
	v_mul_f32_e32 v167, v228, v25
	v_rndne_f32_e32 v164, v164
	v_rndne_f32_e32 v165, v165
	v_rndne_f32_e32 v166, v166
	v_rndne_f32_e32 v167, v167
	v_med3_f32 v164, v164, s71, v183
	v_med3_f32 v165, v165, s71, v183
	v_med3_f32 v166, v166, s71, v183
	v_med3_f32 v167, v167, s71, v183
	v_cvt_i32_f32_e32 v164, v164
	v_cvt_i32_f32_e32 v165, v165
	v_cvt_i32_f32_e32 v166, v166
	v_cvt_i32_f32_e32 v167, v167
	v_and_b32_e32 v164, 0xff, v164
	v_and_b32_e32 v165, 0xff, v165
	v_and_b32_e32 v166, 0xff, v166
	v_lshl_or_b32 v164, v165, 8, v164
	v_lshl_or_b32 v164, v166, 16, v164
	v_lshl_or_b32 v223, v167, 24, v164
	v_pk_fma_f32 v[224:225], v[22:23], v[22:23], v[224:225]
	v_pk_fma_f32 v[226:227], v[24:25], v[24:25], v[226:227]
	global_store_dwordx4 v136, v[218:221], s[86:87] offset:256
	global_store_dwordx2 v137, v[222:223], s[88:89] offset:128
	s_nop 0
	v_add_f32_e32 v224, v224, v225
	v_add_f32_e32 v226, v226, v227
	v_add_f32_e32 v224, v224, v226
	ds_bpermute_b32 v225, v138, v224
	s_waitcnt lgkmcnt(0)
	v_add_f32_e32 v224, v224, v225
	ds_bpermute_b32 v225, v139, v224
	s_waitcnt lgkmcnt(0)
	v_add_f32_e32 v224, v224, v225
	s_and_saveexec_b64 s[32:33], s[6:7]
	global_atomic_add_f32 v134, v224, s[16:17] offset:640
	s_or_b64 exec, exec, s[32:33]
	s_add_u32 s86, s86, 0x20000
	s_addc_u32 s87, s87, 0
	s_add_u32 s88, s88, 0x10000
	s_addc_u32 s89, s89, 0
	s_waitcnt vmcnt(5)
; __device__ __forceinline__ u32x4 pack8(const f32x4 a, const f32x4 b) { u32x4 w; w.x = cvt_pk_bf16(a[0], a[1]); w.y = cvt_pk_bf16(a[2], a[3]); w.z = cvt_pk_bf16(b[0], b[1]); w.w = cvt_pk_bf16(b[2], b[3]); return w; }
;     __device__ __forceinline__ void operator()(const f32x4 (&acc)[2][2][4][2], const pg8::Unit& u, int wr, int wc, int fr, int fq) const {
;     ...
;                 for (int mm = 0; mm < 2; ++mm) { const int m = 2 * mp + mm, row = row0 + ai * 128 + m * 16; float ss = 0.f; const float iq = (127.f / QCLIP) * iqv[mm];
; #pragma unroll
;                     for (int bj = 0; bj < 2; ++bj) { const size_t off = (size_t)row * DM + col0 + bj * 128;
;                         const f32x4 h0 = xr[mm][bj][0] + acc[ai][bj][m][0], h1 = xr[mm][bj][1] + acc[ai][bj][m][1];
;                         *(u32x4*)(HB + off) = pack8(h0, h1);
;                         { f32x4 q0, q1;
; #pragma unroll
;                           for (int ee = 0; ee < 4; ++ee) { q0[ee] = fminf(fmaxf(rintf(h0[ee] * iq), -127.f), 127.f); q1[ee] = fminf(fmaxf(rintf(h1[ee] * iq), -127.f), 127.f); }
;                           *(u32x2*)(HQ + off) = pack8_i8(q0, q1); }
;                         ss += (h0[0] * h0[0] + h0[1] * h0[1]) + (h0[2] * h0[2] + h0[3] * h0[3]) + (h1[0] * h1[0] + h1[1] * h1[1]) + (h1[2] * h1[2] + h1[3] * h1[3]); }
;                     ss += __shfl_xor(ss, 16); ss += __shfl_xor(ss, 32);
;                     if (fq == 0) unsafeAtomicAdd(rss1 + row, ss); }
	v_mul_f32_e32 v228, 0x41e1c71c, v163
	v_pk_add_f32 v[18:19], v[18:19], v[202:203]
	v_pk_add_f32 v[20:21], v[20:21], v[204:205]
	v_cvt_pk_bf16_f32 v218, v18, v19
	v_cvt_pk_bf16_f32 v219, v20, v21
	v_mul_f32_e32 v164, v228, v18
	v_mul_f32_e32 v165, v228, v19
	v_mul_f32_e32 v166, v228, v20
	v_mul_f32_e32 v167, v228, v21
	v_rndne_f32_e32 v164, v164
	v_rndne_f32_e32 v165, v165
	v_rndne_f32_e32 v166, v166
	v_rndne_f32_e32 v167, v167
	v_med3_f32 v164, v164, s71, v183
	v_med3_f32 v165, v165, s71, v183
	v_med3_f32 v166, v166, s71, v183
	v_med3_f32 v167, v167, s71, v183
	v_cvt_i32_f32_e32 v164, v164
	v_cvt_i32_f32_e32 v165, v165
	v_cvt_i32_f32_e32 v166, v166
	v_cvt_i32_f32_e32 v167, v167
	v_and_b32_e32 v164, 0xff, v164
	v_and_b32_e32 v165, 0xff, v165
	v_and_b32_e32 v166, 0xff, v166
	v_lshl_or_b32 v164, v165, 8, v164
	v_lshl_or_b32 v164, v166, 16, v164
	v_lshl_or_b32 v222, v167, 24, v164
	v_pk_mul_f32 v[224:225], v[18:19], v[18:19]
	v_pk_mul_f32 v[226:227], v[20:21], v[20:21]
	v_pk_add_f32 v[14:15], v[14:15], v[206:207]
	v_pk_add_f32 v[16:17], v[16:17], v[208:209]
	v_cvt_pk_bf16_f32 v220, v14, v15
	v_cvt_pk_bf16_f32 v221, v16, v17
	v_mul_f32_e32 v164, v228, v14
	v_mul_f32_e32 v165, v228, v15
	v_mul_f32_e32 v166, v228, v16
	v_mul_f32_e32 v167, v228, v17
	v_rndne_f32_e32 v164, v164
	v_rndne_f32_e32 v165, v165
	v_rndne_f32_e32 v166, v166
	v_rndne_f32_e32 v167, v167
	v_med3_f32 v164, v164, s71, v183
	v_med3_f32 v165, v165, s71, v183
	v_med3_f32 v166, v166, s71, v183
	v_med3_f32 v167, v167, s71, v183
	v_cvt_i32_f32_e32 v164, v164
	v_cvt_i32_f32_e32 v165, v165
	v_cvt_i32_f32_e32 v166, v166
	v_cvt_i32_f32_e32 v167, v167
	v_and_b32_e32 v164, 0xff, v164
	v_and_b32_e32 v165, 0xff, v165
	v_and_b32_e32 v166, 0xff, v166
	v_lshl_or_b32 v164, v165, 8, v164
	v_lshl_or_b32 v164, v166, 16, v164
	v_lshl_or_b32 v223, v167, 24, v164
	v_pk_fma_f32 v[224:225], v[14:15], v[14:15], v[224:225]
	v_pk_fma_f32 v[226:227], v[16:17], v[16:17], v[226:227]
	global_store_dwordx4 v136, v[218:221], s[86:87]
	global_store_dwordx2 v137, v[222:223], s[88:89]
	s_nop 0
	v_pk_add_f32 v[10:11], v[10:11], v[210:211]
	v_pk_add_f32 v[12:13], v[12:13], v[212:213]
	v_cvt_pk_bf16_f32 v218, v10, v11
	v_cvt_pk_bf16_f32 v219, v12, v13
	v_mul_f32_e32 v164, v228, v10
	v_mul_f32_e32 v165, v228, v11
	v_mul_f32_e32 v166, v228, v12
	v_mul_f32_e32 v167, v228, v13
	v_rndne_f32_e32 v164, v164
	v_rndne_f32_e32 v165, v165
	v_rndne_f32_e32 v166, v166
	v_rndne_f32_e32 v167, v167
	v_med3_f32 v164, v164, s71, v183
	v_med3_f32 v165, v165, s71, v183
	v_med3_f32 v166, v166, s71, v183
	v_med3_f32 v167, v167, s71, v183
	v_cvt_i32_f32_e32 v164, v164
	v_cvt_i32_f32_e32 v165, v165
	v_cvt_i32_f32_e32 v166, v166
	v_cvt_i32_f32_e32 v167, v167
	v_and_b32_e32 v164, 0xff, v164
	v_and_b32_e32 v165, 0xff, v165
	v_and_b32_e32 v166, 0xff, v166
	v_lshl_or_b32 v164, v165, 8, v164
	v_lshl_or_b32 v164, v166, 16, v164
	v_lshl_or_b32 v222, v167, 24, v164
	v_pk_fma_f32 v[224:225], v[10:11], v[10:11], v[224:225]
	v_pk_fma_f32 v[226:227], v[12:13], v[12:13], v[226:227]
	v_pk_add_f32 v[6:7], v[6:7], v[214:215]
	v_pk_add_f32 v[8:9], v[8:9], v[216:217]
	v_cvt_pk_bf16_f32 v220, v6, v7
	v_cvt_pk_bf16_f32 v221, v8, v9
	v_mul_f32_e32 v164, v228, v6
	v_mul_f32_e32 v165, v228, v7
	v_mul_f32_e32 v166, v228, v8
	v_mul_f32_e32 v167, v228, v9
	v_rndne_f32_e32 v164, v164
	v_rndne_f32_e32 v165, v165
	v_rndne_f32_e32 v166, v166
	v_rndne_f32_e32 v167, v167
	v_med3_f32 v164, v164, s71, v183
	v_med3_f32 v165, v165, s71, v183
	v_med3_f32 v166, v166, s71, v183
	v_med3_f32 v167, v167, s71, v183
	v_cvt_i32_f32_e32 v164, v164
	v_cvt_i32_f32_e32 v165, v165
	v_cvt_i32_f32_e32 v166, v166
	v_cvt_i32_f32_e32 v167, v167
	v_and_b32_e32 v164, 0xff, v164
	v_and_b32_e32 v165, 0xff, v165
	v_and_b32_e32 v166, 0xff, v166
	v_lshl_or_b32 v164, v165, 8, v164
	v_lshl_or_b32 v164, v166, 16, v164
	v_lshl_or_b32 v223, v167, 24, v164
	v_pk_fma_f32 v[224:225], v[6:7], v[6:7], v[224:225]
	v_pk_fma_f32 v[226:227], v[8:9], v[8:9], v[226:227]
	global_store_dwordx4 v136, v[218:221], s[86:87] offset:256
	global_store_dwordx2 v137, v[222:223], s[88:89] offset:128
	s_nop 0
	v_add_f32_e32 v224, v224, v225
	v_add_f32_e32 v226, v226, v227
	v_add_f32_e32 v224, v224, v226
	ds_bpermute_b32 v225, v138, v224
	s_waitcnt lgkmcnt(0)
	v_add_f32_e32 v224, v224, v225
	ds_bpermute_b32 v225, v139, v224
	s_waitcnt lgkmcnt(0)
	v_add_f32_e32 v224, v224, v225
	s_and_saveexec_b64 s[32:33], s[6:7]
	global_atomic_add_f32 v134, v224, s[16:17] offset:704
	s_or_b64 exec, exec, s[32:33]
	s_nop 1
	s_andn2_b64 vcc, exec, s[8:9]
	s_mov_b64 s[8:9], -1
	s_cbranch_vccnz .LBB0_1124
	s_andn2_b64 vcc, exec, s[24:25]
	s_cbranch_vccnz .LBB0_1123
	s_barrier
	s_branch .LBB0_1123
